# phase B: two-deep next-row prefetch (row rr+2 loaded at the top of step rr into alternating register sets, 128 KB instead of 64 KB in flight per CU); on top of v64
# baseline (speedup 1.0000x reference)
.LBB0_117:
	s_or_b64 exec, exec, s[26:27]
	s_waitcnt lgkmcnt(0)
	s_barrier
	v_ashrrev_i32_e32 v81, 31, v80
	v_lshlrev_b64 v[0:1], 13, v[80:81]
	v_lshl_add_u64 v[84:85], v[70:71], 0, v[0:1]
	s_mov_b64 s[26:27], 0
	v_mov_b32_e32 v82, v80
	s_waitcnt vmcnt(7)
	v_mov_b64_e32 v[0:1], v[60:61]
	s_waitcnt vmcnt(6)
	v_mov_b64_e32 v[4:5], v[56:57]
	s_waitcnt vmcnt(5)
	v_mov_b64_e32 v[8:9], v[52:53]
	s_waitcnt vmcnt(4)
	v_mov_b64_e32 v[12:13], v[48:49]
	v_mov_b64_e32 v[2:3], v[62:63]
	v_mov_b64_e32 v[6:7], v[58:59]
	s_waitcnt vmcnt(3)
	v_mov_b64_e32 v[16:17], v[44:45]
	s_waitcnt vmcnt(2)
	v_mov_b64_e32 v[20:21], v[40:41]
	s_waitcnt vmcnt(1)
	v_mov_b64_e32 v[24:25], v[36:37]
	s_waitcnt vmcnt(0)
	v_mov_b64_e32 v[28:29], v[32:33]
	v_mov_b64_e32 v[10:11], v[54:55]
	v_mov_b64_e32 v[14:15], v[50:51]
	v_mov_b64_e32 v[18:19], v[46:47]
	v_mov_b64_e32 v[22:23], v[42:43]
	v_mov_b64_e32 v[26:27], v[38:39]
	v_mov_b64_e32 v[30:31], v[34:35]
	s_mov_b64 s[60:61], 0x2000
	s_mov_b64 s[64:65], 0x3000
	s_mov_b64 s[98:99], 0x4000
	s_mov_b64 s[100:101], 0x5000
	v_lshl_add_u64 v[218:219], v[84:85], 0, s[60:61]
	v_lshl_add_u64 v[220:221], v[84:85], 0, s[64:65]
	global_load_dwordx4 v[184:187], v[218:219], off nt
	global_load_dwordx4 v[188:191], v[218:219], off offset:1024 nt
	global_load_dwordx4 v[192:195], v[218:219], off offset:2048 nt
	global_load_dwordx4 v[196:199], v[218:219], off offset:3072 nt
	global_load_dwordx4 v[200:203], v[220:221], off nt
	global_load_dwordx4 v[204:207], v[220:221], off offset:1024 nt
	global_load_dwordx4 v[208:211], v[220:221], off offset:2048 nt
	global_load_dwordx4 v[212:215], v[220:221], off offset:3072 nt
	s_branch .LBB0_119
	s_nop 0
	s_nop 0
.LBB0_118:
	s_or_b64 exec, exec, s[34:35]
	s_cmp_eq_u32 s26, 0
	s_cbranch_scc1 .Lb2_w16
	s_cmp_ge_u32 s26, 0xc000
	s_cbranch_scc1 .Lb2_w16
	s_waitcnt vmcnt(24)
	s_branch .Lb2_wd
.Lb2_w16:
	s_waitcnt vmcnt(16)
.Lb2_wd:
	s_bitcmp1_b32 s26, 13
	s_cbranch_scc1 .Lb2_cpA
	v_mov_b64_e32 v[60:61], v[184:185]
	v_mov_b64_e32 v[62:63], v[186:187]
	v_mov_b64_e32 v[56:57], v[188:189]
	v_mov_b64_e32 v[58:59], v[190:191]
	v_mov_b64_e32 v[52:53], v[192:193]
	v_mov_b64_e32 v[54:55], v[194:195]
	v_mov_b64_e32 v[48:49], v[196:197]
	v_mov_b64_e32 v[50:51], v[198:199]
	v_mov_b64_e32 v[44:45], v[200:201]
	v_mov_b64_e32 v[46:47], v[202:203]
	v_mov_b64_e32 v[40:41], v[204:205]
	v_mov_b64_e32 v[42:43], v[206:207]
	v_mov_b64_e32 v[36:37], v[208:209]
	v_mov_b64_e32 v[38:39], v[210:211]
	v_mov_b64_e32 v[32:33], v[212:213]
	v_mov_b64_e32 v[34:35], v[214:215]
	s_branch .Lb2_cpd
.Lb2_cpA:
	v_mov_b64_e32 v[60:61], v[0:1]
	v_mov_b64_e32 v[62:63], v[2:3]
	v_mov_b64_e32 v[56:57], v[4:5]
	v_mov_b64_e32 v[58:59], v[6:7]
	v_mov_b64_e32 v[52:53], v[8:9]
	v_mov_b64_e32 v[54:55], v[10:11]
	v_mov_b64_e32 v[48:49], v[12:13]
	v_mov_b64_e32 v[50:51], v[14:15]
	v_mov_b64_e32 v[44:45], v[16:17]
	v_mov_b64_e32 v[46:47], v[18:19]
	v_mov_b64_e32 v[40:41], v[20:21]
	v_mov_b64_e32 v[42:43], v[22:23]
	v_mov_b64_e32 v[36:37], v[24:25]
	v_mov_b64_e32 v[38:39], v[26:27]
	v_mov_b64_e32 v[32:33], v[28:29]
	v_mov_b64_e32 v[34:35], v[30:31]
.Lb2_cpd:
	s_add_u32 s26, s26, 0x2000
	s_addc_u32 s27, s27, 0
	v_add_u32_e32 v82, 1, v82
	s_cmp_eq_u32 s26, 0x10000
	s_cbranch_scc1 .LBB0_100
.LBB0_119:
	s_cmp_ge_u32 s26, 0xc000
	s_cbranch_scc1 .LBB0_121
	v_lshl_add_u64 v[216:217], v[84:85], 0, s[26:27]
	v_lshl_add_u64 v[218:219], v[216:217], 0, s[98:99]
	v_lshl_add_u64 v[220:221], v[216:217], 0, s[100:101]
	s_bitcmp1_b32 s26, 13
	s_cbranch_scc1 .Lb2_ldB
	global_load_dwordx4 v[0:3], v[218:219], off nt
	global_load_dwordx4 v[4:7], v[218:219], off offset:1024 nt
	global_load_dwordx4 v[8:11], v[218:219], off offset:2048 nt
	global_load_dwordx4 v[12:15], v[218:219], off offset:3072 nt
	global_load_dwordx4 v[16:19], v[220:221], off nt
	global_load_dwordx4 v[20:23], v[220:221], off offset:1024 nt
	global_load_dwordx4 v[24:27], v[220:221], off offset:2048 nt
	global_load_dwordx4 v[28:31], v[220:221], off offset:3072 nt
	s_branch .LBB0_121
.Lb2_ldB:
	global_load_dwordx4 v[184:187], v[218:219], off nt
	global_load_dwordx4 v[188:191], v[218:219], off offset:1024 nt
	global_load_dwordx4 v[192:195], v[218:219], off offset:2048 nt
	global_load_dwordx4 v[196:199], v[218:219], off offset:3072 nt
	global_load_dwordx4 v[200:203], v[220:221], off nt
	global_load_dwordx4 v[204:207], v[220:221], off offset:1024 nt
	global_load_dwordx4 v[208:211], v[220:221], off offset:2048 nt
	global_load_dwordx4 v[212:215], v[220:221], off offset:3072 nt
